# speedup vs baseline: 1.0330x; 1.0043x over previous
.LBB0_542:
	s_add_u32 m0, s101, 0xc810
	s_nop 0
	global_load_lds_dwordx4 v243, s[54:55]
	s_add_u32 m0, s101, 0xe810
	s_nop 0
	global_load_lds_dwordx4 v244, s[54:55]
	v_cmp_le_u32_e32 vcc, s52, v217
	s_and_saveexec_b64 s[8:9], vcc
	s_cbranch_execz .LBB0_548
	s_waitcnt lgkmcnt(1)
	v_mfma_f32_32x32x16_bf16 v[98:113], v[98:101], v[130:133], 0
	ds_read_b128 v[118:121], v187 offset:18432
	ds_read_b128 v[220:223], v187 offset:22528
	s_waitcnt lgkmcnt(1)
	v_mfma_f32_32x32x16_bf16 v[98:113], v[118:121], v[134:137], v[98:113]
	ds_read_b128 v[118:121], v215 offset:18432
	s_waitcnt lgkmcnt(0)
	v_mfma_f32_32x32x16_bf16 v[98:113], v[118:121], v[138:141], v[98:113]
	ds_read_b128 v[118:121], v216 offset:18432
	s_waitcnt lgkmcnt(0)
	v_mfma_f32_32x32x16_bf16 v[98:113], v[118:121], v[142:145], v[98:113]
	v_mfma_f32_32x32x16_bf16 v[114:129], v[114:117], v[130:133], 0
	v_mfma_f32_32x32x16_bf16 v[114:129], v[220:223], v[134:137], v[114:129]
	v_mov_b32_e32 v219, v249
	v_mov_b32_e32 v220, v249
	s_nop 1
	v_permlane32_swap_b32_e32 v219, v220
	v_max_f32_e32 v220, v220, v220
	v_max_f32_e32 v219, v219, v219
	v_max_f32_e32 v219, v219, v220
	v_sub_f32_e32 v220, v219, v192
	v_cmp_ge_f32_e32 vcc, s36, v220
	s_cmp_eq_u64 vcc, exec
	v_max_f32_e32 v220, v192, v192
	s_cselect_b64 vcc, -1, 0
	v_max_f32_e32 v219, v220, v219
	v_cndmask_b32_e32 v219, v219, v192, vcc
	v_sub_f32_e32 v192, v192, v219
	v_mul_f32_e32 v192, 0x3e38aa3b, v192
	v_exp_f32_e32 v220, v192
	v_mul_f32_e32 v192, 0xbe38aa3b, v219
	v_pk_fma_f32 v[96:97], v[96:97], s[78:79], v[192:193] op_sel_hi:[1,0,0]
	ds_read_b128 v[224:227], v215 offset:22528
	v_pk_fma_f32 v[86:87], v[86:87], s[78:79], v[192:193] op_sel_hi:[1,0,0]
	v_pk_fma_f32 v[88:89], v[88:89], s[78:79], v[192:193] op_sel_hi:[1,0,0]
	v_pk_fma_f32 v[90:91], v[90:91], s[78:79], v[192:193] op_sel_hi:[1,0,0]
	v_pk_fma_f32 v[92:93], v[92:93], s[78:79], v[192:193] op_sel_hi:[1,0,0]
	v_pk_fma_f32 v[94:95], v[94:95], s[78:79], v[192:193] op_sel_hi:[1,0,0]
	ds_read_b128 v[162:165], v216 offset:22528
	v_pk_fma_f32 v[84:85], v[84:85], s[78:79], v[192:193] op_sel_hi:[1,0,0]
	s_waitcnt lgkmcnt(1)
	v_mfma_f32_32x32x16_bf16 v[114:129], v[224:227], v[138:141], v[114:129]
	v_fma_f32 v66, v66, s78, v192
	v_fma_f32 v67, v67, s78, v192
	v_fma_f32 v68, v68, s78, v192
	v_fma_f32 v69, v69, s78, v192
	v_exp_f32_e32 v66, v66
	v_exp_f32_e32 v67, v67
	v_exp_f32_e32 v68, v68
	v_exp_f32_e32 v69, v69
	v_pk_fma_f32 v[70:71], v[70:71], s[78:79], v[192:193] op_sel_hi:[1,0,0]
	v_exp_f32_e32 v70, v70
	v_exp_f32_e32 v71, v71
	v_pk_fma_f32 v[72:73], v[72:73], s[78:79], v[192:193] op_sel_hi:[1,0,0]
	v_exp_f32_e32 v84, v84
	v_exp_f32_e32 v72, v72
	v_exp_f32_e32 v73, v73
	s_waitcnt lgkmcnt(0)
	v_mfma_f32_32x32x16_bf16 v[114:129], v[162:165], v[142:145], v[114:129]
	v_fma_f32 v74, v74, s78, v192
	v_fma_f32 v75, v75, s78, v192
	v_fma_f32 v76, v76, s78, v192
	v_fma_f32 v77, v77, s78, v192
	v_exp_f32_e32 v74, v74
	v_exp_f32_e32 v75, v75
	v_exp_f32_e32 v76, v76
	v_exp_f32_e32 v77, v77
	v_pk_fma_f32 v[78:79], v[78:79], s[78:79], v[192:193] op_sel_hi:[1,0,0]
	v_pk_fma_f32 v[80:81], v[80:81], s[78:79], v[192:193] op_sel_hi:[1,0,0]
	v_exp_f32_e32 v78, v78
	v_exp_f32_e32 v79, v79
	v_exp_f32_e32 v80, v80
	v_exp_f32_e32 v81, v81
	v_pk_fma_f32 v[82:83], v[82:83], s[78:79], v[192:193] op_sel_hi:[1,0,0]
	v_exp_f32_e32 v82, v82
	v_exp_f32_e32 v83, v83
	v_exp_f32_e32 v85, v85
	v_exp_f32_e32 v86, v86
	v_exp_f32_e32 v87, v87
	v_exp_f32_e32 v88, v88
	v_exp_f32_e32 v89, v89
	v_exp_f32_e32 v90, v90
	v_exp_f32_e32 v91, v91
	v_exp_f32_e32 v92, v92
	v_exp_f32_e32 v93, v93
	v_exp_f32_e32 v94, v94
	v_exp_f32_e32 v95, v95
	v_exp_f32_e32 v96, v96
	v_exp_f32_e32 v97, v97
	s_cbranch_vccnz .LBB0_547
	s_waitcnt lgkmcnt(0)
	s_and_saveexec_b64 s[60:61], s[2:3]
	ds_write_b32 v207, v220
	s_or_b64 exec, exec, s[60:61]
	s_waitcnt lgkmcnt(0)
	v_add_u32_e32 v164, v206, v194
	ds_read_b128 v[222:225], v164 offset:96
	ds_read_b128 v[226:229], v164 offset:64
	ds_read_b128 v[230:233], v164 offset:32
	ds_read_b128 v[234:237], v164
	s_waitcnt lgkmcnt(0)
	s_waitcnt lgkmcnt(3)
	v_pk_mul_f32 v[62:63], v[62:63], v[222:223]
	s_waitcnt lgkmcnt(2)
	v_pk_mul_f32 v[58:59], v[58:59], v[226:227]
	s_waitcnt lgkmcnt(1)
	v_pk_mul_f32 v[54:55], v[54:55], v[230:231]
	v_pk_mul_f32 v[64:65], v[64:65], v[224:225]
	v_pk_mul_f32 v[60:61], v[60:61], v[228:229]
	v_pk_mul_f32 v[56:57], v[56:57], v[232:233]
	s_waitcnt lgkmcnt(0)
	v_pk_mul_f32 v[52:53], v[52:53], v[236:237]
	v_pk_mul_f32 v[50:51], v[50:51], v[234:235]
	v_pk_mul_f32 v[46:47], v[46:47], v[222:223]
	v_pk_mul_f32 v[42:43], v[42:43], v[226:227]
	v_pk_mul_f32 v[38:39], v[38:39], v[230:231]
	v_pk_mul_f32 v[48:49], v[48:49], v[224:225]
	v_pk_mul_f32 v[44:45], v[44:45], v[228:229]
	v_pk_mul_f32 v[40:41], v[40:41], v[232:233]
	v_pk_mul_f32 v[36:37], v[36:37], v[236:237]
	v_pk_mul_f32 v[34:35], v[34:35], v[234:235]
	v_pk_mul_f32 v[30:31], v[30:31], v[222:223]
	v_pk_mul_f32 v[26:27], v[26:27], v[226:227]
	v_pk_mul_f32 v[22:23], v[22:23], v[230:231]
	v_pk_mul_f32 v[32:33], v[32:33], v[224:225]
	v_pk_mul_f32 v[28:29], v[28:29], v[228:229]
	v_pk_mul_f32 v[24:25], v[24:25], v[232:233]
	v_pk_mul_f32 v[20:21], v[20:21], v[236:237]
	v_pk_mul_f32 v[18:19], v[18:19], v[234:235]
	v_pk_mul_f32 v[14:15], v[14:15], v[222:223]
	v_pk_mul_f32 v[10:11], v[10:11], v[226:227]
	v_pk_mul_f32 v[6:7], v[6:7], v[230:231]
	v_pk_mul_f32 v[16:17], v[16:17], v[224:225]
	v_pk_mul_f32 v[12:13], v[12:13], v[228:229]
	v_pk_mul_f32 v[8:9], v[8:9], v[232:233]
	v_pk_mul_f32 v[4:5], v[4:5], v[236:237]
	v_pk_mul_f32 v[2:3], v[2:3], v[234:235]
.LBB0_547:
	v_add_u32_e32 v164, v200, v202
	ds_read_b128 v[226:229], v164 offset:34816
	ds_read_b128 v[230:233], v164 offset:38912
	ds_read_b128 v[234:237], v164 offset:43008
	ds_read_b128 v[238:241], v164 offset:47104
	v_add_u32_e32 v164, v200, v203
	v_cvt_pk_bf16_f32 v222, v66, v67
	v_cvt_pk_bf16_f32 v223, v68, v69
	v_cvt_pk_bf16_f32 v224, v70, v71
	v_cvt_pk_bf16_f32 v225, v72, v73
	s_waitcnt lgkmcnt(3)
	v_mfma_f32_32x32x16_bf16 v[50:65], v[222:225], v[226:229], v[50:65]
	ds_read_b128 v[226:229], v164 offset:34816
	v_max_f32_e32 v247, v99, v99
	v_add_f32_e32 v156, 0, v66
	v_max_f32_e32 v248, v98, v98
	v_add_f32_e32 v157, 0, v67
	v_add_f32_e32 v156, v68, v156
	v_mov_b32_e32 v192, v219
	s_waitcnt lgkmcnt(3)
	v_mfma_f32_32x32x16_bf16 v[34:49], v[222:225], v[230:233], v[34:49]
	ds_read_b128 v[230:233], v164 offset:38912
	v_max_f32_e32 v247, v248, v247
	v_add_f32_e32 v157, v69, v157
	v_max3_f32 v247, v247, v100, v101
	v_add_f32_e32 v156, v70, v156
	v_add_f32_e32 v157, v71, v157
	s_waitcnt lgkmcnt(3)
	v_mfma_f32_32x32x16_bf16 v[18:33], v[222:225], v[234:237], v[18:33]
	ds_read_b128 v[234:237], v164 offset:43008
	v_max3_f32 v247, v247, v102, v103
	v_add_f32_e32 v156, v72, v156
	v_max3_f32 v247, v247, v104, v105
	v_add_f32_e32 v157, v73, v157
	v_add_f32_e32 v156, v74, v156
	s_waitcnt lgkmcnt(3)
	v_mfma_f32_32x32x16_bf16 v[2:17], v[222:225], v[238:241], v[2:17]
	ds_read_b128 v[238:241], v164 offset:47104
	v_max3_f32 v247, v247, v106, v107
	v_add_f32_e32 v157, v75, v157
	v_max3_f32 v247, v247, v108, v109
	v_add_f32_e32 v156, v76, v156
	v_add_f32_e32 v157, v77, v157
	v_add_u32_e32 v164, v200, v204
	v_cvt_pk_bf16_f32 v222, v74, v75
	v_cvt_pk_bf16_f32 v223, v76, v77
	v_cvt_pk_bf16_f32 v224, v78, v79
	v_cvt_pk_bf16_f32 v225, v80, v81
	s_waitcnt lgkmcnt(3)
	v_mfma_f32_32x32x16_bf16 v[50:65], v[222:225], v[226:229], v[50:65]
	ds_read_b128 v[226:229], v164 offset:34816
	v_max3_f32 v247, v247, v110, v111
	v_add_f32_e32 v156, v78, v156
	v_max3_f32 v254, v247, v112, v113
	v_add_f32_e32 v157, v79, v157
	v_add_f32_e32 v156, v80, v156
	s_waitcnt lgkmcnt(3)
	v_mfma_f32_32x32x16_bf16 v[34:49], v[222:225], v[230:233], v[34:49]
	ds_read_b128 v[230:233], v164 offset:38912
	v_max3_f32 v250, v254, v114, v115
	v_add_f32_e32 v157, v81, v157
	v_max3_f32 v250, v250, v116, v117
	v_add_f32_e32 v156, v82, v156
	v_add_f32_e32 v157, v83, v157
	s_waitcnt lgkmcnt(3)
	v_mfma_f32_32x32x16_bf16 v[18:33], v[222:225], v[234:237], v[18:33]
	ds_read_b128 v[234:237], v164 offset:43008
	v_max3_f32 v250, v250, v118, v119
	v_add_f32_e32 v156, v84, v156
	v_max3_f32 v250, v250, v120, v121
	v_add_f32_e32 v157, v85, v157
	v_add_f32_e32 v156, v86, v156
	s_waitcnt lgkmcnt(3)
	v_mfma_f32_32x32x16_bf16 v[2:17], v[222:225], v[238:241], v[2:17]
	ds_read_b128 v[238:241], v164 offset:47104
	v_max3_f32 v250, v250, v122, v123
	v_add_f32_e32 v157, v87, v157
	v_max3_f32 v250, v250, v124, v125
	v_add_f32_e32 v156, v88, v156
	v_add_f32_e32 v157, v89, v157
	v_add_u32_e32 v164, v200, v205
	v_cvt_pk_bf16_f32 v222, v82, v83
	v_cvt_pk_bf16_f32 v223, v84, v85
	v_cvt_pk_bf16_f32 v224, v86, v87
	v_cvt_pk_bf16_f32 v225, v88, v89
	s_waitcnt lgkmcnt(3)
	v_mfma_f32_32x32x16_bf16 v[50:65], v[222:225], v[226:229], v[50:65]
	ds_read_b128 v[226:229], v164 offset:34816
	v_max3_f32 v250, v250, v126, v127
	v_add_f32_e32 v156, v90, v156
	v_max3_f32 v250, v250, v128, v129
	v_add_f32_e32 v157, v91, v157
	v_add_f32_e32 v156, v92, v156
	s_waitcnt lgkmcnt(3)
	v_mfma_f32_32x32x16_bf16 v[34:49], v[222:225], v[230:233], v[34:49]
	ds_read_b128 v[230:233], v164 offset:38912
	v_add_f32_e32 v157, v93, v157
	v_add_f32_e32 v156, v94, v156
	v_add_f32_e32 v157, v95, v157
	s_waitcnt lgkmcnt(3)
	v_mfma_f32_32x32x16_bf16 v[18:33], v[222:225], v[234:237], v[18:33]
	ds_read_b128 v[234:237], v164 offset:43008
	v_add_f32_e32 v156, v96, v156
	v_add_f32_e32 v157, v97, v157
	v_add_f32_e32 v156, v156, v157
	v_mov_b32_e32 v157, v156
	s_nop 1
	v_permlane32_swap_b32_e32 v156, v157
	v_add_f32_e32 v162, v156, v157
	s_waitcnt lgkmcnt(3)
	v_mfma_f32_32x32x16_bf16 v[2:17], v[222:225], v[238:241], v[2:17]
	ds_read_b128 v[238:241], v164 offset:47104
	v_cvt_pk_bf16_f32 v222, v90, v91
	v_cvt_pk_bf16_f32 v223, v92, v93
	v_cvt_pk_bf16_f32 v224, v94, v95
	v_cvt_pk_bf16_f32 v225, v96, v97
	v_cndmask_b32_e64 v164, v220, 1.0, vcc
	v_fmac_f32_e32 v162, v218, v164
	s_waitcnt lgkmcnt(3)
	v_mfma_f32_32x32x16_bf16 v[50:65], v[222:225], v[226:229], v[50:65]
	v_mov_b32_e32 v218, v162
	s_waitcnt lgkmcnt(2)
	v_mfma_f32_32x32x16_bf16 v[34:49], v[222:225], v[230:233], v[34:49]
	s_waitcnt lgkmcnt(1)
	v_mfma_f32_32x32x16_bf16 v[18:33], v[222:225], v[234:237], v[18:33]
	s_waitcnt lgkmcnt(0)
	v_mfma_f32_32x32x16_bf16 v[2:17], v[222:225], v[238:241], v[2:17]

.LBB0_557:
	s_waitcnt lgkmcnt(1)
	v_mfma_f32_32x32x16_bf16 v[66:81], v[66:69], v[130:133], 0
	ds_read_b128 v[86:89], v187 offset:2048
	ds_read_b128 v[188:191], v187 offset:6144
	s_waitcnt lgkmcnt(1)
	v_mfma_f32_32x32x16_bf16 v[66:81], v[86:89], v[134:137], v[66:81]
	ds_read_b128 v[86:89], v215 offset:2048
	s_waitcnt lgkmcnt(0)
	v_mfma_f32_32x32x16_bf16 v[66:81], v[86:89], v[138:141], v[66:81]
	ds_read_b128 v[86:89], v216 offset:2048
	s_waitcnt lgkmcnt(0)
	v_mfma_f32_32x32x16_bf16 v[66:81], v[86:89], v[142:145], v[66:81]
	v_mfma_f32_32x32x16_bf16 v[82:97], v[82:85], v[130:133], 0
	v_mfma_f32_32x32x16_bf16 v[82:97], v[188:191], v[134:137], v[82:97]
	v_mov_b32_e32 v188, v250
	v_mov_b32_e32 v189, v250
	s_nop 1
	v_permlane32_swap_b32_e32 v188, v189
	v_max_f32_e32 v189, v189, v189
	v_max_f32_e32 v188, v188, v188
	v_max_f32_e32 v188, v188, v189
	v_sub_f32_e32 v189, v188, v192
	v_cmp_ge_f32_e32 vcc, s36, v189
	s_cmp_eq_u64 vcc, exec
	v_max_f32_e32 v189, v192, v192
	s_cselect_b64 vcc, -1, 0
	v_max_f32_e32 v188, v189, v188
	v_cndmask_b32_e32 v189, v188, v192, vcc
	v_sub_f32_e32 v188, v192, v189
	v_mul_f32_e32 v188, 0x3e38aa3b, v188
	v_exp_f32_e32 v190, v188
	v_mul_f32_e32 v188, 0xbe38aa3b, v189
	v_pk_fma_f32 v[128:129], v[128:129], s[78:79], v[188:189] op_sel_hi:[1,0,0]
	ds_read_b128 v[220:223], v215 offset:6144
	v_pk_fma_f32 v[118:119], v[118:119], s[78:79], v[188:189] op_sel_hi:[1,0,0]
	v_pk_fma_f32 v[120:121], v[120:121], s[78:79], v[188:189] op_sel_hi:[1,0,0]
	v_pk_fma_f32 v[122:123], v[122:123], s[78:79], v[188:189] op_sel_hi:[1,0,0]
	v_pk_fma_f32 v[124:125], v[124:125], s[78:79], v[188:189] op_sel_hi:[1,0,0]
	v_pk_fma_f32 v[126:127], v[126:127], s[78:79], v[188:189] op_sel_hi:[1,0,0]
	ds_read_b128 v[162:165], v216 offset:6144
	v_pk_fma_f32 v[108:109], v[108:109], s[78:79], v[188:189] op_sel_hi:[1,0,0]
	v_pk_fma_f32 v[110:111], v[110:111], s[78:79], v[188:189] op_sel_hi:[1,0,0]
	v_pk_fma_f32 v[112:113], v[112:113], s[78:79], v[188:189] op_sel_hi:[1,0,0]
	v_pk_fma_f32 v[114:115], v[114:115], s[78:79], v[188:189] op_sel_hi:[1,0,0]
	v_pk_fma_f32 v[116:117], v[116:117], s[78:79], v[188:189] op_sel_hi:[1,0,0]
	s_waitcnt lgkmcnt(1)
	v_mfma_f32_32x32x16_bf16 v[82:97], v[220:223], v[138:141], v[82:97]
	v_fma_f32 v98, v98, s78, v188
	v_fma_f32 v99, v99, s78, v188
	v_fma_f32 v100, v100, s78, v188
	v_fma_f32 v101, v101, s78, v188
	v_exp_f32_e32 v98, v98
	v_exp_f32_e32 v99, v99
	v_exp_f32_e32 v100, v100
	v_exp_f32_e32 v101, v101
	v_pk_fma_f32 v[102:103], v[102:103], s[78:79], v[188:189] op_sel_hi:[1,0,0]
	v_pk_fma_f32 v[104:105], v[104:105], s[78:79], v[188:189] op_sel_hi:[1,0,0]
	v_exp_f32_e32 v102, v102
	v_exp_f32_e32 v103, v103
	v_exp_f32_e32 v104, v104
	v_exp_f32_e32 v105, v105
	v_pk_fma_f32 v[106:107], v[106:107], s[78:79], v[188:189] op_sel_hi:[1,0,0]
	v_exp_f32_e32 v106, v106
	v_exp_f32_e32 v107, v107
	v_exp_f32_e32 v108, v108
	v_exp_f32_e32 v109, v109
	v_exp_f32_e32 v110, v110
	v_exp_f32_e32 v111, v111
	v_exp_f32_e32 v112, v112
	v_exp_f32_e32 v113, v113
	v_exp_f32_e32 v114, v114
	v_exp_f32_e32 v115, v115
	v_exp_f32_e32 v116, v116
	v_exp_f32_e32 v117, v117
	v_exp_f32_e32 v118, v118
	v_exp_f32_e32 v119, v119
	v_exp_f32_e32 v120, v120
	v_exp_f32_e32 v121, v121
	s_waitcnt lgkmcnt(0)
	v_mfma_f32_32x32x16_bf16 v[82:97], v[162:165], v[142:145], v[82:97]
	v_exp_f32_e32 v122, v122
	v_exp_f32_e32 v123, v123
	v_exp_f32_e32 v124, v124
	v_exp_f32_e32 v125, v125
	v_exp_f32_e32 v126, v126
	v_exp_f32_e32 v127, v127
	v_exp_f32_e32 v128, v128
	v_exp_f32_e32 v129, v129
	s_cbranch_vccnz .LBB0_561
	s_waitcnt lgkmcnt(0)
	s_and_saveexec_b64 s[62:63], s[2:3]
	ds_write_b32 v207, v190
	s_or_b64 exec, exec, s[62:63]
	s_waitcnt lgkmcnt(0)
	v_add_u32_e32 v164, v206, v194
	ds_read_b128 v[220:223], v164 offset:96
	ds_read_b128 v[224:227], v164 offset:64
	ds_read_b128 v[228:231], v164 offset:32
	ds_read_b128 v[232:235], v164
	s_waitcnt lgkmcnt(0)
	s_waitcnt lgkmcnt(3)
	v_pk_mul_f32 v[62:63], v[62:63], v[220:221]
	s_waitcnt lgkmcnt(2)
	v_pk_mul_f32 v[58:59], v[58:59], v[224:225]
	s_waitcnt lgkmcnt(1)
	v_pk_mul_f32 v[54:55], v[54:55], v[228:229]
	v_pk_mul_f32 v[64:65], v[64:65], v[222:223]
	v_pk_mul_f32 v[60:61], v[60:61], v[226:227]
	v_pk_mul_f32 v[56:57], v[56:57], v[230:231]
	s_waitcnt lgkmcnt(0)
	v_pk_mul_f32 v[52:53], v[52:53], v[234:235]
	v_pk_mul_f32 v[50:51], v[50:51], v[232:233]
	v_pk_mul_f32 v[46:47], v[46:47], v[220:221]
	v_pk_mul_f32 v[42:43], v[42:43], v[224:225]
	v_pk_mul_f32 v[38:39], v[38:39], v[228:229]
	v_pk_mul_f32 v[48:49], v[48:49], v[222:223]
	v_pk_mul_f32 v[44:45], v[44:45], v[226:227]
	v_pk_mul_f32 v[40:41], v[40:41], v[230:231]
	v_pk_mul_f32 v[36:37], v[36:37], v[234:235]
	v_pk_mul_f32 v[34:35], v[34:35], v[232:233]
	v_pk_mul_f32 v[30:31], v[30:31], v[220:221]
	v_pk_mul_f32 v[26:27], v[26:27], v[224:225]
	v_pk_mul_f32 v[22:23], v[22:23], v[228:229]
	v_pk_mul_f32 v[32:33], v[32:33], v[222:223]
	v_pk_mul_f32 v[28:29], v[28:29], v[226:227]
	v_pk_mul_f32 v[24:25], v[24:25], v[230:231]
	v_pk_mul_f32 v[20:21], v[20:21], v[234:235]
	v_pk_mul_f32 v[18:19], v[18:19], v[232:233]
	v_pk_mul_f32 v[14:15], v[14:15], v[220:221]
	v_pk_mul_f32 v[10:11], v[10:11], v[224:225]
	v_pk_mul_f32 v[6:7], v[6:7], v[228:229]
	v_pk_mul_f32 v[16:17], v[16:17], v[222:223]
	v_pk_mul_f32 v[12:13], v[12:13], v[226:227]
	v_pk_mul_f32 v[8:9], v[8:9], v[230:231]
	v_pk_mul_f32 v[4:5], v[4:5], v[234:235]
	v_pk_mul_f32 v[2:3], v[2:3], v[232:233]
.LBB0_561:
	v_add_u32_e32 v164, v200, v202
	ds_read_b128 v[224:227], v164 offset:51200
	ds_read_b128 v[228:231], v164 offset:55296
	ds_read_b128 v[232:235], v164 offset:59392
	ds_read_b128 v[236:239], v164 offset:63488
	v_add_u32_e32 v164, v200, v203
	v_cvt_pk_bf16_f32 v220, v98, v99
	v_cvt_pk_bf16_f32 v221, v100, v101
	v_cvt_pk_bf16_f32 v222, v102, v103
	v_cvt_pk_bf16_f32 v223, v104, v105
	s_waitcnt lgkmcnt(3)
	v_mfma_f32_32x32x16_bf16 v[50:65], v[220:223], v[224:227], v[50:65]
	ds_read_b128 v[224:227], v164 offset:51200
	v_max_f32_e32 v247, v67, v67
	v_add_f32_e32 v156, 0, v98
	v_max_f32_e32 v248, v66, v66
	v_add_f32_e32 v157, 0, v99
	v_add_f32_e32 v156, v100, v156
	v_mov_b32_e32 v192, v189
	s_waitcnt lgkmcnt(3)
	v_mfma_f32_32x32x16_bf16 v[34:49], v[220:223], v[228:231], v[34:49]
	ds_read_b128 v[228:231], v164 offset:55296
	v_max_f32_e32 v247, v248, v247
	v_add_f32_e32 v157, v101, v157
	v_max3_f32 v247, v247, v68, v69
	v_add_f32_e32 v156, v102, v156
	v_add_f32_e32 v157, v103, v157
	s_waitcnt lgkmcnt(3)
	v_mfma_f32_32x32x16_bf16 v[18:33], v[220:223], v[232:235], v[18:33]
	ds_read_b128 v[232:235], v164 offset:59392
	v_max3_f32 v247, v247, v70, v71
	v_add_f32_e32 v156, v104, v156
	v_max3_f32 v247, v247, v72, v73
	v_add_f32_e32 v157, v105, v157
	v_add_f32_e32 v156, v106, v156
	s_waitcnt lgkmcnt(3)
	v_mfma_f32_32x32x16_bf16 v[2:17], v[220:223], v[236:239], v[2:17]
	ds_read_b128 v[236:239], v164 offset:63488
	v_max3_f32 v247, v247, v74, v75
	v_add_f32_e32 v157, v107, v157
	v_max3_f32 v247, v247, v76, v77
	v_add_f32_e32 v156, v108, v156
	v_add_f32_e32 v157, v109, v157
	v_add_u32_e32 v164, v200, v204
	v_cvt_pk_bf16_f32 v220, v106, v107
	v_cvt_pk_bf16_f32 v221, v108, v109
	v_cvt_pk_bf16_f32 v222, v110, v111
	v_cvt_pk_bf16_f32 v223, v112, v113
	s_waitcnt lgkmcnt(3)
	v_mfma_f32_32x32x16_bf16 v[50:65], v[220:223], v[224:227], v[50:65]
	ds_read_b128 v[224:227], v164 offset:51200
	v_max3_f32 v247, v247, v78, v79
	v_add_f32_e32 v156, v110, v156
	v_max3_f32 v249, v247, v80, v81
	v_add_f32_e32 v157, v111, v157
	v_add_f32_e32 v156, v112, v156
	s_waitcnt lgkmcnt(3)
	v_mfma_f32_32x32x16_bf16 v[34:49], v[220:223], v[228:231], v[34:49]
	ds_read_b128 v[228:231], v164 offset:55296
	v_max3_f32 v249, v249, v82, v83
	v_add_f32_e32 v157, v113, v157
	v_max3_f32 v249, v249, v84, v85
	v_add_f32_e32 v156, v114, v156
	v_add_f32_e32 v157, v115, v157
	s_waitcnt lgkmcnt(3)
	v_mfma_f32_32x32x16_bf16 v[18:33], v[220:223], v[232:235], v[18:33]
	ds_read_b128 v[232:235], v164 offset:59392
	v_max3_f32 v249, v249, v86, v87
	v_add_f32_e32 v156, v116, v156
	v_max3_f32 v249, v249, v88, v89
	v_add_f32_e32 v157, v117, v157
	v_add_f32_e32 v156, v118, v156
	s_waitcnt lgkmcnt(3)
	v_mfma_f32_32x32x16_bf16 v[2:17], v[220:223], v[236:239], v[2:17]
	ds_read_b128 v[236:239], v164 offset:63488
	v_max3_f32 v249, v249, v90, v91
	v_add_f32_e32 v157, v119, v157
	v_max3_f32 v249, v249, v92, v93
	v_add_f32_e32 v156, v120, v156
	v_add_f32_e32 v157, v121, v157
	v_add_u32_e32 v164, v200, v205
	v_cvt_pk_bf16_f32 v220, v114, v115
	v_cvt_pk_bf16_f32 v221, v116, v117
	v_cvt_pk_bf16_f32 v222, v118, v119
	v_cvt_pk_bf16_f32 v223, v120, v121
	s_waitcnt lgkmcnt(3)
	v_mfma_f32_32x32x16_bf16 v[50:65], v[220:223], v[224:227], v[50:65]
	ds_read_b128 v[224:227], v164 offset:51200
	v_max3_f32 v249, v249, v94, v95
	v_add_f32_e32 v156, v122, v156
	v_max3_f32 v249, v249, v96, v97
	v_add_f32_e32 v157, v123, v157
	v_add_f32_e32 v156, v124, v156
	s_waitcnt lgkmcnt(3)
	v_mfma_f32_32x32x16_bf16 v[34:49], v[220:223], v[228:231], v[34:49]
	ds_read_b128 v[228:231], v164 offset:55296
	v_add_f32_e32 v157, v125, v157
	v_add_f32_e32 v156, v126, v156
	v_add_f32_e32 v157, v127, v157
	s_waitcnt lgkmcnt(3)
	v_mfma_f32_32x32x16_bf16 v[18:33], v[220:223], v[232:235], v[18:33]
	ds_read_b128 v[232:235], v164 offset:59392
	v_add_f32_e32 v156, v128, v156
	v_add_f32_e32 v157, v129, v157
	v_add_f32_e32 v156, v156, v157
	v_mov_b32_e32 v157, v156
	s_nop 1
	v_permlane32_swap_b32_e32 v156, v157
	v_add_f32_e32 v162, v156, v157
	s_waitcnt lgkmcnt(3)
	v_mfma_f32_32x32x16_bf16 v[2:17], v[220:223], v[236:239], v[2:17]
	ds_read_b128 v[236:239], v164 offset:63488
	v_cvt_pk_bf16_f32 v220, v122, v123
	v_cvt_pk_bf16_f32 v221, v124, v125
	v_cvt_pk_bf16_f32 v222, v126, v127
	v_cvt_pk_bf16_f32 v223, v128, v129
	v_cndmask_b32_e64 v164, v190, 1.0, vcc
	v_fmac_f32_e32 v162, v218, v164
	s_waitcnt lgkmcnt(3)
	v_mfma_f32_32x32x16_bf16 v[50:65], v[220:223], v[224:227], v[50:65]
	v_mov_b32_e32 v218, v162
	s_waitcnt lgkmcnt(2)
	v_mfma_f32_32x32x16_bf16 v[34:49], v[220:223], v[228:231], v[34:49]
	s_waitcnt lgkmcnt(1)
	v_mfma_f32_32x32x16_bf16 v[18:33], v[220:223], v[232:235], v[18:33]
	s_waitcnt lgkmcnt(0)
	v_mfma_f32_32x32x16_bf16 v[2:17], v[220:223], v[236:239], v[2:17]
	s_or_b64 exec, exec, s[60:61]
	s_andn2_b64 vcc, exec, s[58:59]
	s_cbranch_vccnz .LBB0_554

.LBB0_1318:
	s_add_u32 m0, s101, 0xc810
	s_nop 0
	global_load_lds_dwordx4 v243, s[40:41]
	s_add_u32 m0, s101, 0xe810
	s_nop 0
	global_load_lds_dwordx4 v244, s[40:41]
	v_cmp_le_u32_e32 vcc, s52, v214
	s_and_saveexec_b64 s[8:9], vcc
	s_cbranch_execz .LBB0_1324
	s_waitcnt lgkmcnt(1)
	v_mfma_f32_32x32x16_bf16 v[82:97], v[82:85], v[130:133], 0
	ds_read_b128 v[118:121], v183 offset:18432
	ds_read_b128 v[218:221], v183 offset:22528
	s_waitcnt lgkmcnt(1)
	v_mfma_f32_32x32x16_bf16 v[82:97], v[118:121], v[134:137], v[82:97]
	v_mov_b32_e32 v122, v249
	v_mov_b32_e32 v118, v249
	s_nop 1
	v_permlane32_swap_b32_e32 v122, v118
	ds_read_b128 v[222:225], v212 offset:22528
	ds_read_b128 v[226:229], v213 offset:22528
	v_max_f32_e32 v123, v118, v118
	ds_read_b128 v[118:121], v212 offset:18432
	s_waitcnt lgkmcnt(0)
	v_mfma_f32_32x32x16_bf16 v[82:97], v[118:121], v[138:141], v[82:97]
	v_max_f32_e32 v118, v122, v122
	v_max_f32_e32 v118, v118, v123
	v_sub_f32_e32 v120, v118, v188
	v_cmp_ge_f32_e32 vcc, s70, v120
	v_max_f32_e32 v119, v188, v188
	s_cmp_eq_u64 vcc, exec
	v_max_f32_e32 v118, v119, v118
	s_cselect_b64 vcc, -1, 0
	v_cndmask_b32_e32 v216, v118, v188, vcc
	v_sub_f32_e32 v118, v188, v216
	v_mul_f32_e32 v188, 0xbe38aa3b, v216
	v_mul_f32_e32 v189, 0x3e38aa3b, v118
	ds_read_b128 v[118:121], v213 offset:18432
	s_waitcnt lgkmcnt(0)
	v_mfma_f32_32x32x16_bf16 v[82:97], v[118:121], v[142:145], v[82:97]
	v_fma_f32 v66, v66, s18, v188
	v_fma_f32 v67, v67, s18, v188
	v_fma_f32 v68, v68, s18, v188
	v_fma_f32 v69, v69, s18, v188
	v_exp_f32_e32 v66, v66
	v_exp_f32_e32 v67, v67
	v_pk_fma_f32 v[70:71], v[70:71], s[18:19], v[188:189] op_sel_hi:[1,0,0]
	v_exp_f32_e32 v68, v68
	v_exp_f32_e32 v69, v69
	v_pk_fma_f32 v[72:73], v[72:73], s[18:19], v[188:189] op_sel_hi:[1,0,0]
	v_exp_f32_e32 v70, v70
	v_exp_f32_e32 v71, v71
	v_pk_fma_f32 v[74:75], v[74:75], s[18:19], v[188:189] op_sel_hi:[1,0,0]
	v_exp_f32_e32 v72, v72
	v_exp_f32_e32 v73, v73
	v_exp_f32_e32 v74, v74
	v_exp_f32_e32 v75, v75
	v_exp_f32_e32 v217, v189
	v_mfma_f32_32x32x16_bf16 v[114:129], v[114:117], v[130:133], 0
	v_mfma_f32_32x32x16_bf16 v[114:129], v[218:221], v[134:137], v[114:129]
	v_mfma_f32_32x32x16_bf16 v[114:129], v[222:225], v[138:141], v[114:129]
	v_mfma_f32_32x32x16_bf16 v[114:129], v[226:229], v[142:145], v[114:129]
	v_fma_f32 v76, v76, s18, v188
	v_fma_f32 v77, v77, s18, v188
	v_fma_f32 v78, v78, s18, v188
	v_fma_f32 v79, v79, s18, v188
	v_exp_f32_e32 v76, v76
	v_exp_f32_e32 v77, v77
	v_pk_fma_f32 v[80:81], v[80:81], s[18:19], v[188:189] op_sel_hi:[1,0,0]
	v_exp_f32_e32 v78, v78
	v_exp_f32_e32 v79, v79
	v_exp_f32_e32 v80, v80
	v_exp_f32_e32 v81, v81
	v_pk_fma_f32 v[98:99], v[98:99], s[18:19], v[188:189] op_sel_hi:[1,0,0]
	v_pk_fma_f32 v[100:101], v[100:101], s[18:19], v[188:189] op_sel_hi:[1,0,0]
	v_exp_f32_e32 v98, v98
	v_exp_f32_e32 v99, v99
	v_exp_f32_e32 v100, v100
	v_exp_f32_e32 v101, v101
	v_pk_fma_f32 v[102:103], v[102:103], s[18:19], v[188:189] op_sel_hi:[1,0,0]
	v_pk_fma_f32 v[104:105], v[104:105], s[18:19], v[188:189] op_sel_hi:[1,0,0]
	v_exp_f32_e32 v102, v102
	v_exp_f32_e32 v103, v103
	v_exp_f32_e32 v104, v104
	v_exp_f32_e32 v105, v105
	v_pk_fma_f32 v[106:107], v[106:107], s[18:19], v[188:189] op_sel_hi:[1,0,0]
	v_pk_fma_f32 v[108:109], v[108:109], s[18:19], v[188:189] op_sel_hi:[1,0,0]
	v_exp_f32_e32 v106, v106
	v_exp_f32_e32 v107, v107
	v_exp_f32_e32 v108, v108
	v_exp_f32_e32 v109, v109
	v_pk_fma_f32 v[110:111], v[110:111], s[18:19], v[188:189] op_sel_hi:[1,0,0]
	v_exp_f32_e32 v110, v110
	v_exp_f32_e32 v111, v111
	v_pk_fma_f32 v[112:113], v[112:113], s[18:19], v[188:189] op_sel_hi:[1,0,0]
	s_nop 0
	v_exp_f32_e32 v112, v112
	v_exp_f32_e32 v113, v113
	s_cbranch_vccnz .LBB0_1323
	s_waitcnt lgkmcnt(0)
	s_and_saveexec_b64 s[56:57], s[2:3]
	ds_write_b32 v204, v217
	s_or_b64 exec, exec, s[56:57]
	s_waitcnt lgkmcnt(0)
	v_add_u32_e32 v230, v203, v191
	ds_read_b128 v[218:221], v230 offset:96
	ds_read_b128 v[222:225], v230 offset:64
	ds_read_b128 v[226:229], v230 offset:32
	ds_read_b128 v[230:233], v230
	s_waitcnt lgkmcnt(0)
	s_waitcnt lgkmcnt(3)
	v_pk_mul_f32 v[62:63], v[62:63], v[218:219]
	s_waitcnt lgkmcnt(2)
	v_pk_mul_f32 v[58:59], v[58:59], v[222:223]
	s_waitcnt lgkmcnt(1)
	v_pk_mul_f32 v[54:55], v[54:55], v[226:227]
	v_pk_mul_f32 v[64:65], v[64:65], v[220:221]
	v_pk_mul_f32 v[60:61], v[60:61], v[224:225]
	v_pk_mul_f32 v[56:57], v[56:57], v[228:229]
	s_waitcnt lgkmcnt(0)
	v_pk_mul_f32 v[52:53], v[52:53], v[232:233]
	v_pk_mul_f32 v[50:51], v[50:51], v[230:231]
	v_pk_mul_f32 v[46:47], v[46:47], v[218:219]
	v_pk_mul_f32 v[42:43], v[42:43], v[222:223]
	v_pk_mul_f32 v[38:39], v[38:39], v[226:227]
	v_pk_mul_f32 v[48:49], v[48:49], v[220:221]
	v_pk_mul_f32 v[44:45], v[44:45], v[224:225]
	v_pk_mul_f32 v[40:41], v[40:41], v[228:229]
	v_pk_mul_f32 v[36:37], v[36:37], v[232:233]
	v_pk_mul_f32 v[34:35], v[34:35], v[230:231]
	v_pk_mul_f32 v[30:31], v[30:31], v[218:219]
	v_pk_mul_f32 v[26:27], v[26:27], v[222:223]
	v_pk_mul_f32 v[22:23], v[22:23], v[226:227]
	v_pk_mul_f32 v[32:33], v[32:33], v[220:221]
	v_pk_mul_f32 v[28:29], v[28:29], v[224:225]
	v_pk_mul_f32 v[24:25], v[24:25], v[228:229]
	v_pk_mul_f32 v[20:21], v[20:21], v[232:233]
	v_pk_mul_f32 v[18:19], v[18:19], v[230:231]
	v_pk_mul_f32 v[14:15], v[14:15], v[218:219]
	v_pk_mul_f32 v[10:11], v[10:11], v[222:223]
	v_pk_mul_f32 v[6:7], v[6:7], v[226:227]
	v_pk_mul_f32 v[16:17], v[16:17], v[220:221]
	v_pk_mul_f32 v[12:13], v[12:13], v[224:225]
	v_pk_mul_f32 v[8:9], v[8:9], v[228:229]
	v_pk_mul_f32 v[4:5], v[4:5], v[232:233]
	v_pk_mul_f32 v[2:3], v[2:3], v[230:231]
.LBB0_1323:
	v_add_u32_e32 v234, v197, v199
	ds_read_b128 v[222:225], v234 offset:34816
	ds_read_b128 v[226:229], v234 offset:38912
	ds_read_b128 v[230:233], v234 offset:43008
	ds_read_b128 v[234:237], v234 offset:47104
	v_add_u32_e32 v238, v197, v200
	v_cvt_pk_bf16_f32 v218, v66, v67
	v_cvt_pk_bf16_f32 v219, v68, v69
	v_cvt_pk_bf16_f32 v220, v70, v71
	v_cvt_pk_bf16_f32 v221, v72, v73
	v_cndmask_b32_e64 v217, v217, 1.0, vcc
	s_waitcnt lgkmcnt(3)
	v_mfma_f32_32x32x16_bf16 v[50:65], v[218:221], v[222:225], v[50:65]
	ds_read_b128 v[222:225], v238 offset:34816
	v_max_f32_e32 v247, v83, v83
	v_add_f32_e32 v156, 0, v66
	v_max_f32_e32 v248, v82, v82
	v_add_f32_e32 v157, 0, v67
	v_add_f32_e32 v156, v68, v156
	v_mov_b32_e32 v188, v216
	s_waitcnt lgkmcnt(3)
	v_mfma_f32_32x32x16_bf16 v[34:49], v[218:221], v[226:229], v[34:49]
	ds_read_b128 v[226:229], v238 offset:38912
	v_max_f32_e32 v247, v248, v247
	v_add_f32_e32 v157, v69, v157
	v_max3_f32 v247, v247, v84, v85
	v_add_f32_e32 v156, v70, v156
	v_add_f32_e32 v157, v71, v157
	s_waitcnt lgkmcnt(3)
	v_mfma_f32_32x32x16_bf16 v[18:33], v[218:221], v[230:233], v[18:33]
	ds_read_b128 v[230:233], v238 offset:43008
	v_max3_f32 v247, v247, v86, v87
	v_add_f32_e32 v156, v72, v156
	v_max3_f32 v247, v247, v88, v89
	v_add_f32_e32 v157, v73, v157
	v_add_f32_e32 v156, v74, v156
	s_waitcnt lgkmcnt(3)
	v_mfma_f32_32x32x16_bf16 v[2:17], v[218:221], v[234:237], v[2:17]
	ds_read_b128 v[234:237], v238 offset:47104
	v_max3_f32 v247, v247, v90, v91
	v_add_f32_e32 v157, v75, v157
	v_max3_f32 v247, v247, v92, v93
	v_add_f32_e32 v156, v76, v156
	v_add_f32_e32 v157, v77, v157
	v_add_u32_e32 v238, v197, v201
	v_cvt_pk_bf16_f32 v218, v74, v75
	v_cvt_pk_bf16_f32 v219, v76, v77
	v_cvt_pk_bf16_f32 v220, v78, v79
	v_cvt_pk_bf16_f32 v221, v80, v81
	s_waitcnt lgkmcnt(3)
	v_mfma_f32_32x32x16_bf16 v[50:65], v[218:221], v[222:225], v[50:65]
	ds_read_b128 v[222:225], v238 offset:34816
	v_max3_f32 v247, v247, v94, v95
	v_add_f32_e32 v156, v78, v156
	v_max3_f32 v250, v247, v96, v97
	v_add_f32_e32 v157, v79, v157
	v_add_f32_e32 v156, v80, v156
	s_waitcnt lgkmcnt(3)
	v_mfma_f32_32x32x16_bf16 v[34:49], v[218:221], v[226:229], v[34:49]
	ds_read_b128 v[226:229], v238 offset:38912
	v_max3_f32 v247, v250, v114, v115
	v_add_f32_e32 v157, v81, v157
	v_max3_f32 v247, v247, v116, v117
	v_add_f32_e32 v156, v98, v156
	v_add_f32_e32 v157, v99, v157
	s_waitcnt lgkmcnt(3)
	v_mfma_f32_32x32x16_bf16 v[18:33], v[218:221], v[230:233], v[18:33]
	ds_read_b128 v[230:233], v238 offset:43008
	v_max3_f32 v247, v247, v118, v119
	v_add_f32_e32 v156, v100, v156
	v_max3_f32 v247, v247, v120, v121
	v_add_f32_e32 v157, v101, v157
	v_add_f32_e32 v156, v102, v156
	s_waitcnt lgkmcnt(3)
	v_mfma_f32_32x32x16_bf16 v[2:17], v[218:221], v[234:237], v[2:17]
	ds_read_b128 v[234:237], v238 offset:47104
	v_max3_f32 v247, v247, v122, v123
	v_add_f32_e32 v157, v103, v157
	v_max3_f32 v247, v247, v124, v125
	v_add_f32_e32 v156, v104, v156
	v_add_f32_e32 v157, v105, v157
	v_add_u32_e32 v238, v197, v202
	v_cvt_pk_bf16_f32 v218, v98, v99
	v_cvt_pk_bf16_f32 v219, v100, v101
	v_cvt_pk_bf16_f32 v220, v102, v103
	v_cvt_pk_bf16_f32 v221, v104, v105
	s_waitcnt lgkmcnt(3)
	v_mfma_f32_32x32x16_bf16 v[50:65], v[218:221], v[222:225], v[50:65]
	ds_read_b128 v[222:225], v238 offset:34816
	v_max3_f32 v247, v247, v126, v127
	v_add_f32_e32 v156, v106, v156
	v_max3_f32 v250, v247, v128, v129
	v_add_f32_e32 v157, v107, v157
	v_add_f32_e32 v156, v108, v156
	s_waitcnt lgkmcnt(3)
	v_mfma_f32_32x32x16_bf16 v[34:49], v[218:221], v[226:229], v[34:49]
	ds_read_b128 v[226:229], v238 offset:38912
	v_add_f32_e32 v157, v109, v157
	v_add_f32_e32 v156, v110, v156
	v_add_f32_e32 v157, v111, v157
	s_waitcnt lgkmcnt(3)
	v_mfma_f32_32x32x16_bf16 v[18:33], v[218:221], v[230:233], v[18:33]
	ds_read_b128 v[230:233], v238 offset:43008
	v_add_f32_e32 v156, v112, v156
	v_add_f32_e32 v157, v113, v157
	v_add_f32_e32 v156, v156, v157
	v_mov_b32_e32 v157, v156
	s_nop 1
	v_permlane32_swap_b32_e32 v156, v157
	v_add_f32_e32 v189, v156, v157
	v_fmac_f32_e32 v189, v215, v217
	v_mov_b32_e32 v215, v189
	s_waitcnt lgkmcnt(3)
	v_mfma_f32_32x32x16_bf16 v[2:17], v[218:221], v[234:237], v[2:17]
	ds_read_b128 v[234:237], v238 offset:47104
	v_cvt_pk_bf16_f32 v218, v106, v107
	v_cvt_pk_bf16_f32 v219, v108, v109
	v_cvt_pk_bf16_f32 v220, v110, v111
	v_cvt_pk_bf16_f32 v221, v112, v113
	s_waitcnt lgkmcnt(3)
	v_mfma_f32_32x32x16_bf16 v[50:65], v[218:221], v[222:225], v[50:65]
	s_waitcnt lgkmcnt(2)
	v_mfma_f32_32x32x16_bf16 v[34:49], v[218:221], v[226:229], v[34:49]
	s_waitcnt lgkmcnt(1)
	v_mfma_f32_32x32x16_bf16 v[18:33], v[218:221], v[230:233], v[18:33]
	s_waitcnt lgkmcnt(0)
	v_mfma_f32_32x32x16_bf16 v[2:17], v[218:221], v[234:237], v[2:17]

.LBB0_1333:
	s_waitcnt lgkmcnt(1)
	v_mfma_f32_32x32x16_bf16 v[66:81], v[66:69], v[130:133], 0
	ds_read_b128 v[102:105], v183 offset:2048
	ds_read_b128 v[216:219], v183 offset:6144
	s_waitcnt lgkmcnt(1)
	v_mfma_f32_32x32x16_bf16 v[66:81], v[102:105], v[134:137], v[66:81]
	v_mov_b32_e32 v106, v250
	v_mov_b32_e32 v102, v250
	s_nop 1
	v_permlane32_swap_b32_e32 v106, v102
	ds_read_b128 v[220:223], v212 offset:6144
	ds_read_b128 v[224:227], v213 offset:6144
	v_max_f32_e32 v107, v102, v102
	ds_read_b128 v[102:105], v212 offset:2048
	s_waitcnt lgkmcnt(0)
	v_mfma_f32_32x32x16_bf16 v[66:81], v[102:105], v[138:141], v[66:81]
	v_max_f32_e32 v102, v106, v106
	v_max_f32_e32 v102, v102, v107
	v_sub_f32_e32 v104, v102, v188
	v_cmp_ge_f32_e32 vcc, s70, v104
	v_max_f32_e32 v103, v188, v188
	s_cmp_eq_u64 vcc, exec
	v_max_f32_e32 v102, v103, v102
	s_cselect_b64 vcc, -1, 0
	v_cndmask_b32_e32 v186, v102, v188, vcc
	v_sub_f32_e32 v102, v188, v186
	v_mul_f32_e32 v184, 0xbe38aa3b, v186
	v_mul_f32_e32 v185, 0x3e38aa3b, v102
	ds_read_b128 v[102:105], v213 offset:2048
	s_waitcnt lgkmcnt(0)
	v_mfma_f32_32x32x16_bf16 v[66:81], v[102:105], v[142:145], v[66:81]
	v_fma_f32 v82, v82, s18, v184
	v_fma_f32 v83, v83, s18, v184
	v_fma_f32 v84, v84, s18, v184
	v_fma_f32 v85, v85, s18, v184
	v_exp_f32_e32 v82, v82
	v_exp_f32_e32 v83, v83
	v_pk_fma_f32 v[86:87], v[86:87], s[18:19], v[184:185] op_sel_hi:[1,0,0]
	v_exp_f32_e32 v84, v84
	v_exp_f32_e32 v85, v85
	v_pk_fma_f32 v[88:89], v[88:89], s[18:19], v[184:185] op_sel_hi:[1,0,0]
	v_exp_f32_e32 v86, v86
	v_exp_f32_e32 v87, v87
	v_pk_fma_f32 v[90:91], v[90:91], s[18:19], v[184:185] op_sel_hi:[1,0,0]
	v_exp_f32_e32 v88, v88
	v_exp_f32_e32 v89, v89
	v_exp_f32_e32 v90, v90
	v_exp_f32_e32 v91, v91
	v_exp_f32_e32 v187, v185
	v_mfma_f32_32x32x16_bf16 v[98:113], v[98:101], v[130:133], 0
	v_mfma_f32_32x32x16_bf16 v[98:113], v[216:219], v[134:137], v[98:113]
	v_mfma_f32_32x32x16_bf16 v[98:113], v[220:223], v[138:141], v[98:113]
	v_mfma_f32_32x32x16_bf16 v[98:113], v[224:227], v[142:145], v[98:113]
	v_fma_f32 v92, v92, s18, v184
	v_fma_f32 v93, v93, s18, v184
	v_fma_f32 v94, v94, s18, v184
	v_fma_f32 v95, v95, s18, v184
	v_exp_f32_e32 v92, v92
	v_exp_f32_e32 v93, v93
	v_pk_fma_f32 v[96:97], v[96:97], s[18:19], v[184:185] op_sel_hi:[1,0,0]
	v_exp_f32_e32 v94, v94
	v_exp_f32_e32 v95, v95
	v_exp_f32_e32 v96, v96
	v_exp_f32_e32 v97, v97
	v_pk_fma_f32 v[114:115], v[114:115], s[18:19], v[184:185] op_sel_hi:[1,0,0]
	v_pk_fma_f32 v[116:117], v[116:117], s[18:19], v[184:185] op_sel_hi:[1,0,0]
	v_exp_f32_e32 v114, v114
	v_exp_f32_e32 v115, v115
	v_exp_f32_e32 v116, v116
	v_exp_f32_e32 v117, v117
	v_pk_fma_f32 v[118:119], v[118:119], s[18:19], v[184:185] op_sel_hi:[1,0,0]
	v_pk_fma_f32 v[120:121], v[120:121], s[18:19], v[184:185] op_sel_hi:[1,0,0]
	v_exp_f32_e32 v118, v118
	v_exp_f32_e32 v119, v119
	v_exp_f32_e32 v120, v120
	v_exp_f32_e32 v121, v121
	v_pk_fma_f32 v[122:123], v[122:123], s[18:19], v[184:185] op_sel_hi:[1,0,0]
	v_pk_fma_f32 v[124:125], v[124:125], s[18:19], v[184:185] op_sel_hi:[1,0,0]
	v_exp_f32_e32 v122, v122
	v_exp_f32_e32 v123, v123
	v_exp_f32_e32 v124, v124
	v_exp_f32_e32 v125, v125
	v_pk_fma_f32 v[126:127], v[126:127], s[18:19], v[184:185] op_sel_hi:[1,0,0]
	v_exp_f32_e32 v126, v126
	v_exp_f32_e32 v127, v127
	v_pk_fma_f32 v[128:129], v[128:129], s[18:19], v[184:185] op_sel_hi:[1,0,0]
	s_nop 0
	v_exp_f32_e32 v128, v128
	v_exp_f32_e32 v129, v129
	s_cbranch_vccnz .LBB0_1337
	s_waitcnt lgkmcnt(0)
	s_and_saveexec_b64 s[58:59], s[2:3]
	ds_write_b32 v204, v187
	s_or_b64 exec, exec, s[58:59]
	s_waitcnt lgkmcnt(0)
	v_add_u32_e32 v188, v203, v191
	ds_read_b128 v[216:219], v188 offset:96
	ds_read_b128 v[220:223], v188 offset:64
	ds_read_b128 v[224:227], v188 offset:32
	ds_read_b128 v[228:231], v188
	s_waitcnt lgkmcnt(0)
	s_waitcnt lgkmcnt(3)
	v_pk_mul_f32 v[62:63], v[62:63], v[216:217]
	s_waitcnt lgkmcnt(2)
	v_pk_mul_f32 v[58:59], v[58:59], v[220:221]
	s_waitcnt lgkmcnt(1)
	v_pk_mul_f32 v[54:55], v[54:55], v[224:225]
	v_pk_mul_f32 v[64:65], v[64:65], v[218:219]
	v_pk_mul_f32 v[60:61], v[60:61], v[222:223]
	v_pk_mul_f32 v[56:57], v[56:57], v[226:227]
	s_waitcnt lgkmcnt(0)
	v_pk_mul_f32 v[52:53], v[52:53], v[230:231]
	v_pk_mul_f32 v[50:51], v[50:51], v[228:229]
	v_pk_mul_f32 v[46:47], v[46:47], v[216:217]
	v_pk_mul_f32 v[42:43], v[42:43], v[220:221]
	v_pk_mul_f32 v[38:39], v[38:39], v[224:225]
	v_pk_mul_f32 v[48:49], v[48:49], v[218:219]
	v_pk_mul_f32 v[44:45], v[44:45], v[222:223]
	v_pk_mul_f32 v[40:41], v[40:41], v[226:227]
	v_pk_mul_f32 v[36:37], v[36:37], v[230:231]
	v_pk_mul_f32 v[34:35], v[34:35], v[228:229]
	v_pk_mul_f32 v[30:31], v[30:31], v[216:217]
	v_pk_mul_f32 v[26:27], v[26:27], v[220:221]
	v_pk_mul_f32 v[22:23], v[22:23], v[224:225]
	v_pk_mul_f32 v[32:33], v[32:33], v[218:219]
	v_pk_mul_f32 v[28:29], v[28:29], v[222:223]
	v_pk_mul_f32 v[24:25], v[24:25], v[226:227]
	v_pk_mul_f32 v[20:21], v[20:21], v[230:231]
	v_pk_mul_f32 v[18:19], v[18:19], v[228:229]
	v_pk_mul_f32 v[14:15], v[14:15], v[216:217]
	v_pk_mul_f32 v[10:11], v[10:11], v[220:221]
	v_pk_mul_f32 v[6:7], v[6:7], v[224:225]
	v_pk_mul_f32 v[16:17], v[16:17], v[218:219]
	v_pk_mul_f32 v[12:13], v[12:13], v[222:223]
	v_pk_mul_f32 v[8:9], v[8:9], v[226:227]
	v_pk_mul_f32 v[4:5], v[4:5], v[230:231]
	v_pk_mul_f32 v[2:3], v[2:3], v[228:229]
.LBB0_1337:
	v_add_u32_e32 v188, v197, v199
	ds_read_b128 v[220:223], v188 offset:51200
	ds_read_b128 v[224:227], v188 offset:55296
	ds_read_b128 v[228:231], v188 offset:59392
	ds_read_b128 v[232:235], v188 offset:63488
	v_add_u32_e32 v188, v197, v200
	v_cvt_pk_bf16_f32 v216, v82, v83
	v_cvt_pk_bf16_f32 v217, v84, v85
	v_cvt_pk_bf16_f32 v218, v86, v87
	v_cvt_pk_bf16_f32 v219, v88, v89
	v_cndmask_b32_e64 v187, v187, 1.0, vcc
	s_waitcnt lgkmcnt(3)
	v_mfma_f32_32x32x16_bf16 v[50:65], v[216:219], v[220:223], v[50:65]
	ds_read_b128 v[220:223], v188 offset:51200
	v_max_f32_e32 v247, v67, v67
	v_add_f32_e32 v156, 0, v82
	v_max_f32_e32 v248, v66, v66
	v_add_f32_e32 v157, 0, v83
	v_add_f32_e32 v156, v84, v156
	s_waitcnt lgkmcnt(3)
	v_mfma_f32_32x32x16_bf16 v[34:49], v[216:219], v[224:227], v[34:49]
	ds_read_b128 v[224:227], v188 offset:55296
	v_max_f32_e32 v247, v248, v247
	v_add_f32_e32 v157, v85, v157
	v_max3_f32 v247, v247, v68, v69
	v_add_f32_e32 v156, v86, v156
	v_add_f32_e32 v157, v87, v157
	s_waitcnt lgkmcnt(3)
	v_mfma_f32_32x32x16_bf16 v[18:33], v[216:219], v[228:231], v[18:33]
	ds_read_b128 v[228:231], v188 offset:59392
	v_max3_f32 v247, v247, v70, v71
	v_add_f32_e32 v156, v88, v156
	v_max3_f32 v247, v247, v72, v73
	v_add_f32_e32 v157, v89, v157
	v_add_f32_e32 v156, v90, v156
	s_waitcnt lgkmcnt(3)
	v_mfma_f32_32x32x16_bf16 v[2:17], v[216:219], v[232:235], v[2:17]
	ds_read_b128 v[232:235], v188 offset:63488
	v_max3_f32 v247, v247, v74, v75
	v_add_f32_e32 v157, v91, v157
	v_max3_f32 v247, v247, v76, v77
	v_add_f32_e32 v156, v92, v156
	v_add_f32_e32 v157, v93, v157
	v_add_u32_e32 v188, v197, v201
	v_cvt_pk_bf16_f32 v216, v90, v91
	v_cvt_pk_bf16_f32 v217, v92, v93
	v_cvt_pk_bf16_f32 v218, v94, v95
	v_cvt_pk_bf16_f32 v219, v96, v97
	s_waitcnt lgkmcnt(3)
	v_mfma_f32_32x32x16_bf16 v[50:65], v[216:219], v[220:223], v[50:65]
	ds_read_b128 v[220:223], v188 offset:51200
	v_max3_f32 v247, v247, v78, v79
	v_add_f32_e32 v156, v94, v156
	v_max3_f32 v249, v247, v80, v81
	v_add_f32_e32 v157, v95, v157
	v_add_f32_e32 v156, v96, v156
	s_waitcnt lgkmcnt(3)
	v_mfma_f32_32x32x16_bf16 v[34:49], v[216:219], v[224:227], v[34:49]
	ds_read_b128 v[224:227], v188 offset:55296
	v_max3_f32 v247, v249, v98, v99
	v_add_f32_e32 v157, v97, v157
	v_max3_f32 v247, v247, v100, v101
	v_add_f32_e32 v156, v114, v156
	v_add_f32_e32 v157, v115, v157
	s_waitcnt lgkmcnt(3)
	v_mfma_f32_32x32x16_bf16 v[18:33], v[216:219], v[228:231], v[18:33]
	ds_read_b128 v[228:231], v188 offset:59392
	v_max3_f32 v247, v247, v102, v103
	v_add_f32_e32 v156, v116, v156
	v_max3_f32 v247, v247, v104, v105
	v_add_f32_e32 v157, v117, v157
	v_add_f32_e32 v156, v118, v156
	s_waitcnt lgkmcnt(3)
	v_mfma_f32_32x32x16_bf16 v[2:17], v[216:219], v[232:235], v[2:17]
	ds_read_b128 v[232:235], v188 offset:63488
	v_max3_f32 v247, v247, v106, v107
	v_add_f32_e32 v157, v119, v157
	v_max3_f32 v247, v247, v108, v109
	v_add_f32_e32 v156, v120, v156
	v_add_f32_e32 v157, v121, v157
	v_add_u32_e32 v188, v197, v202
	v_cvt_pk_bf16_f32 v216, v114, v115
	v_cvt_pk_bf16_f32 v217, v116, v117
	v_cvt_pk_bf16_f32 v218, v118, v119
	v_cvt_pk_bf16_f32 v219, v120, v121
	s_waitcnt lgkmcnt(3)
	v_mfma_f32_32x32x16_bf16 v[50:65], v[216:219], v[220:223], v[50:65]
	ds_read_b128 v[220:223], v188 offset:51200
	v_max3_f32 v247, v247, v110, v111
	v_add_f32_e32 v156, v122, v156
	v_max3_f32 v249, v247, v112, v113
	v_add_f32_e32 v157, v123, v157
	v_add_f32_e32 v156, v124, v156
	s_waitcnt lgkmcnt(3)
	v_mfma_f32_32x32x16_bf16 v[34:49], v[216:219], v[224:227], v[34:49]
	ds_read_b128 v[224:227], v188 offset:55296
	v_add_f32_e32 v157, v125, v157
	v_add_f32_e32 v156, v126, v156
	v_add_f32_e32 v157, v127, v157
	s_waitcnt lgkmcnt(3)
	v_mfma_f32_32x32x16_bf16 v[18:33], v[216:219], v[228:231], v[18:33]
	ds_read_b128 v[228:231], v188 offset:59392
	v_add_f32_e32 v156, v128, v156
	v_add_f32_e32 v157, v129, v157
	v_add_f32_e32 v156, v156, v157
	v_mov_b32_e32 v157, v156
	s_nop 1
	v_permlane32_swap_b32_e32 v156, v157
	v_add_f32_e32 v184, v156, v157
	v_fmac_f32_e32 v184, v215, v187
	v_mov_b32_e32 v215, v184
	s_waitcnt lgkmcnt(3)
	v_mfma_f32_32x32x16_bf16 v[2:17], v[216:219], v[232:235], v[2:17]
	ds_read_b128 v[232:235], v188 offset:63488
	v_cvt_pk_bf16_f32 v216, v122, v123
	v_cvt_pk_bf16_f32 v217, v124, v125
	v_cvt_pk_bf16_f32 v218, v126, v127
	v_cvt_pk_bf16_f32 v219, v128, v129
	v_mov_b32_e32 v188, v186
	s_waitcnt lgkmcnt(3)
	v_mfma_f32_32x32x16_bf16 v[50:65], v[216:219], v[220:223], v[50:65]
	s_waitcnt lgkmcnt(2)
	v_mfma_f32_32x32x16_bf16 v[34:49], v[216:219], v[224:227], v[34:49]
	s_waitcnt lgkmcnt(1)
	v_mfma_f32_32x32x16_bf16 v[18:33], v[216:219], v[228:231], v[18:33]
	s_waitcnt lgkmcnt(0)
	v_mfma_f32_32x32x16_bf16 v[2:17], v[216:219], v[232:235], v[2:17]
	s_or_b64 exec, exec, s[56:57]
	s_andn2_b64 vcc, exec, s[54:55]
	s_cbranch_vccnz .LBB0_1330
